# GLU item GEMM k-loop: 8 weight-fragment loads hoisted to loop top with counted vmcnt
# baseline (speedup 1.0000x reference)
; DEV float sigmoid_f(float x) { return rcp_f(1.f + __expf(-x)); }
; DEV float silu_f(float x) { return x * rcp_f(1.f + __expf(-x)); }
; template <int K, int NT, class Epi>
; DEV void small_gemm(const Params& p, const Ctx& cx, const char* As, int astride, const bf16_t* __restrict__ Bt, int n0, Epi epi) {
;     ...
; #pragma unroll 2
;   for (int k0 = 0; k0 < K; k0 += 32) {
;     bf16x8 af[4];
; #pragma unroll
;     for (int i = 0; i < 4; ++i) af[i] = *(const bf16x8*)(As + (i * 16 + fr) * astride + (k0 + fq * 8) * 2);
; #pragma unroll
;     for (int jn = 0; jn < NT; ++jn) {
;       bf16x8 bf = *(const bf16x8*)(Bt + (size_t)(n0 + jn * 16 + fr) * K + k0 + fq * 8);
; #pragma unroll
;       for (int i = 0; i < 4; ++i) acc[i][jn] = __builtin_amdgcn_mfma_f32_16x16x32_f16(bf, af[i], acc[i][jn], 0, 0, 0);
;     }
;   }
; #pragma unroll
;   for (int i = 0; i < 4; ++i)
; #pragma unroll
;     for (int jn = 0; jn < NT; ++jn) epi(i * 16 + fr, n0 + jn * 16 + fq * 4, acc[i][jn]);
; DEV void glu_item(const Params& p, const Ctx& cx, int l, int tile, char* smem) {
;     ...
;   small_gemm<512, 4>(p, cx, smem, 1040, Bt, (tid >> 6) * 64, [&](int m, int n, f32x4 v) {
;     int row = row0 + m;
;     float4 y = *(const float4*)(S5Y + (size_t)row * 512 + n);
;     float4 bb = *(const float4*)(bg + n);
;     h16x4 gt = *(const h16x4*)(zrest + (size_t)row * ZR + 512 + n);
;     uint2 o;
;     o.x = pack_bf2(y.x * sigmoid_f(v[0] + bb.x) * silu_f((float)gt[0]), y.y * sigmoid_f(v[1] + bb.y) * silu_f((float)gt[1]));
;     o.y = pack_bf2(y.z * sigmoid_f(v[2] + bb.z) * silu_f((float)gt[2]), y.w * sigmoid_f(v[3] + bb.w) * silu_f((float)gt[3]));
;     *(uint2*)(ym + (size_t)row * D + n) = o;
.LBB0_138:
	v_lshl_add_u64 v[72:73], v[64:65], 0, v[128:129]
	v_lshl_add_u64 v[172:173], v[66:67], 0, v[128:129]
	v_lshl_add_u64 v[174:175], v[68:69], 0, v[128:129]
	v_lshl_add_u64 v[208:209], v[70:71], 0, v[128:129]
	v_add_co_u32_e32 v102, vcc, s4, v72
	ds_read_b128 v[82:85], v80
	ds_read_b128 v[86:89], v80 offset:16640
	v_addc_co_u32_e32 v103, vcc, 0, v73, vcc
	v_add_co_u32_e32 v104, vcc, s4, v172
	ds_read_b128 v[90:93], v80 offset:33280
	ds_read_b128 v[94:97], v80 offset:49920
	v_addc_co_u32_e32 v105, vcc, 0, v173, vcc
	v_add_co_u32_e32 v74, vcc, s4, v174
	v_lshl_add_u64 v[64:65], v[64:65], 0, s[12:13]
	v_lshl_add_u64 v[66:67], v[66:67], 0, s[12:13]
	v_addc_co_u32_e32 v75, vcc, 0, v175, vcc
	v_add_co_u32_e32 v72, vcc, s4, v208
	v_lshl_add_u64 v[68:69], v[68:69], 0, s[12:13]
	v_lshl_add_u64 v[70:71], v[70:71], 0, s[12:13]
	v_addc_co_u32_e32 v73, vcc, 0, v209, vcc
	global_load_dwordx4 v[176:179], v[102:103], off
	global_load_dwordx4 v[180:183], v[104:105], off
	global_load_dwordx4 v[184:187], v[74:75], off
	global_load_dwordx4 v[188:191], v[72:73], off
	global_load_dwordx4 v[192:195], v[102:103], off offset:64
	global_load_dwordx4 v[196:199], v[104:105], off offset:64
	global_load_dwordx4 v[200:203], v[74:75], off offset:64
	global_load_dwordx4 v[204:207], v[72:73], off offset:64
	s_add_i32 s9, s9, 64
	s_cmpk_lt_u32 s9, 0x1e0
	s_waitcnt vmcnt(7) lgkmcnt(3)
	v_mfma_f32_16x16x32_f16 v[60:63], v[176:179], v[82:85], v[60:63]
	s_waitcnt lgkmcnt(2)
	v_mfma_f32_16x16x32_f16 v[44:47], v[176:179], v[86:89], v[44:47]
	s_waitcnt lgkmcnt(1)
	v_mfma_f32_16x16x32_f16 v[28:31], v[176:179], v[90:93], v[28:31]
	s_waitcnt lgkmcnt(0)
	v_mfma_f32_16x16x32_f16 v[12:15], v[176:179], v[94:97], v[12:15]
	s_waitcnt vmcnt(6)
	v_mfma_f32_16x16x32_f16 v[56:59], v[180:183], v[82:85], v[56:59]
	v_mfma_f32_16x16x32_f16 v[40:43], v[180:183], v[86:89], v[40:43]
	v_mfma_f32_16x16x32_f16 v[24:27], v[180:183], v[90:93], v[24:27]
	v_mfma_f32_16x16x32_f16 v[8:11], v[180:183], v[94:97], v[8:11]
	s_waitcnt vmcnt(5)
	v_mfma_f32_16x16x32_f16 v[52:55], v[184:187], v[82:85], v[52:55]
	v_mfma_f32_16x16x32_f16 v[36:39], v[184:187], v[86:89], v[36:39]
	v_mfma_f32_16x16x32_f16 v[20:23], v[184:187], v[90:93], v[20:23]
	v_mfma_f32_16x16x32_f16 v[4:7], v[184:187], v[94:97], v[4:7]
	s_waitcnt vmcnt(4)
	v_mfma_f32_16x16x32_f16 v[48:51], v[188:191], v[82:85], v[48:51]
	v_mfma_f32_16x16x32_f16 v[32:35], v[188:191], v[86:89], v[32:35]
	v_mfma_f32_16x16x32_f16 v[16:19], v[188:191], v[90:93], v[16:19]
	v_mfma_f32_16x16x32_f16 v[0:3], v[188:191], v[94:97], v[0:3]
	ds_read_b128 v[82:85], v80 offset:64
	ds_read_b128 v[86:89], v80 offset:16704
	ds_read_b128 v[90:93], v80 offset:33344
	ds_read_b128 v[94:97], v80 offset:49984
	v_add_u32_e32 v80, 0x80, v80
	s_waitcnt vmcnt(3) lgkmcnt(3)
	v_mfma_f32_16x16x32_f16 v[60:63], v[192:195], v[82:85], v[60:63]
	s_waitcnt lgkmcnt(2)
	v_mfma_f32_16x16x32_f16 v[44:47], v[192:195], v[86:89], v[44:47]
	s_waitcnt lgkmcnt(1)
	v_mfma_f32_16x16x32_f16 v[28:31], v[192:195], v[90:93], v[28:31]
	s_waitcnt lgkmcnt(0)
	v_mfma_f32_16x16x32_f16 v[12:15], v[192:195], v[94:97], v[12:15]
	s_waitcnt vmcnt(2)
	v_mfma_f32_16x16x32_f16 v[56:59], v[196:199], v[82:85], v[56:59]
	v_mfma_f32_16x16x32_f16 v[40:43], v[196:199], v[86:89], v[40:43]
	v_mfma_f32_16x16x32_f16 v[24:27], v[196:199], v[90:93], v[24:27]
	v_mfma_f32_16x16x32_f16 v[8:11], v[196:199], v[94:97], v[8:11]
	s_waitcnt vmcnt(1)
	v_mfma_f32_16x16x32_f16 v[52:55], v[200:203], v[82:85], v[52:55]
	v_mfma_f32_16x16x32_f16 v[36:39], v[200:203], v[86:89], v[36:39]
	v_mfma_f32_16x16x32_f16 v[20:23], v[200:203], v[90:93], v[20:23]
	v_mfma_f32_16x16x32_f16 v[4:7], v[200:203], v[94:97], v[4:7]
	s_waitcnt vmcnt(0)
	v_mfma_f32_16x16x32_f16 v[48:51], v[204:207], v[82:85], v[48:51]
	v_mfma_f32_16x16x32_f16 v[32:35], v[204:207], v[86:89], v[32:35]
	v_mfma_f32_16x16x32_f16 v[16:19], v[204:207], v[90:93], v[16:19]
	v_mfma_f32_16x16x32_f16 v[0:3], v[204:207], v[94:97], v[0:3]
	s_cbranch_scc1 .LBB0_138
	v_and_b32_e32 v64, 0xffffffc0, v79
	v_or_b32_e32 v68, s8, v76
	v_lshl_or_b32 v66, v77, 2, v64
	v_ashrrev_i32_e32 v69, 31, v68
	v_readlane_b32 s22, v241, 38
	v_lshlrev_b64 v[64:65], 11, v[68:69]
	v_readlane_b32 s23, v241, 39
	v_ashrrev_i32_e32 v67, 31, v66
	v_lshlrev_b64 v[72:73], 2, v[66:67]
	v_lshl_add_u64 v[64:65], s[22:23], 0, v[64:65]
	v_lshl_add_u64 v[74:75], v[64:65], 0, v[72:73]
	v_lshl_add_u64 v[64:65], s[68:69], 0, v[72:73]
	global_load_dwordx4 v[80:83], v[64:65], off
	v_readlane_b32 s4, v241, 40
	v_readlane_b32 s5, v241, 41
	v_lshlrev_b64 v[66:67], 1, v[66:67]
	global_load_dwordx4 v[84:87], v[74:75], off
	v_mov_b64_e32 v[70:71], s[4:5]
	v_mad_i64_i32 v[76:77], s[4:5], v68, s98, v[70:71]
	v_lshl_add_u64 v[76:77], v[76:77], 0, v[66:67]
	global_load_dwordx2 v[88:89], v[76:77], off offset:1024
	v_readlane_b32 s8, v241, 28
	v_readlane_b32 s9, v241, 29
	s_mov_b64 s[84:85], 0x60
	s_waitcnt vmcnt(2)
	v_add_f32_e32 v60, v60, v80
	v_add_f32_e32 v61, v61, v81
	v_mul_f32_e32 v60, 0xbfb8aa3b, v60
	v_mul_f32_e32 v61, 0xbfb8aa3b, v61
	v_exp_f32_e32 v60, v60
	v_exp_f32_e32 v61, v61
	v_add_f32_e32 v60, 1.0, v60
	v_add_f32_e32 v61, 1.0, v61
	v_rcp_f32_e32 v60, v60
	v_rcp_f32_e32 v61, v61
	s_waitcnt vmcnt(0)
; DEV float sigmoid_f(float x) { return rcp_f(1.f + __expf(-x)); }
; DEV float silu_f(float x) { return x * rcp_f(1.f + __expf(-x)); }
; DEV void glu_item(const Params& p, const Ctx& cx, int l, int tile, char* smem) {
;     ...
;   small_gemm<512, 4>(p, cx, smem, 1040, Bt, (tid >> 6) * 64, [&](int m, int n, f32x4 v) {
;     int row = row0 + m;
;     float4 y = *(const float4*)(S5Y + (size_t)row * 512 + n);
;     float4 bb = *(const float4*)(bg + n);
;     h16x4 gt = *(const h16x4*)(zrest + (size_t)row * ZR + 512 + n);
;     uint2 o;
;     o.x = pack_bf2(y.x * sigmoid_f(v[0] + bb.x) * silu_f((float)gt[0]), y.y * sigmoid_f(v[1] + bb.y) * silu_f((float)gt[1]));
;     o.y = pack_bf2(y.z * sigmoid_f(v[2] + bb.z) * silu_f((float)gt[2]), y.w * sigmoid_f(v[3] + bb.w) * silu_f((float)gt[3]));
;     *(uint2*)(ym + (size_t)row * D + n) = o;
;   });
	v_cvt_f32_f16_e32 v80, v88
	v_cvt_f32_f16_sdwa v81, v88 dst_sel:DWORD dst_unused:UNUSED_PAD src0_sel:WORD_1
	v_pk_mul_f32 v[60:61], v[84:85], v[60:61]
	v_mul_f32_e32 v88, 0xbfb8aa3b, v80
	v_mul_f32_e32 v84, 0xbfb8aa3b, v81
	v_exp_f32_e32 v88, v88
	v_exp_f32_e32 v84, v84
	v_add_f32_e32 v88, 1.0, v88
	v_add_f32_e32 v84, 1.0, v84
	v_rcp_f32_e32 v90, v88
	v_rcp_f32_e32 v91, v84
	s_nop 0
	v_pk_mul_f32 v[80:81], v[90:91], v[80:81]
	s_nop 0
	v_pk_mul_f32 v[60:61], v[60:61], v[80:81]
	s_nop 0
	v_cvt_pk_f16_f32 v80, v60, v61
	v_add_f32_e32 v60, v62, v82
	v_cvt_f32_f16_e32 v62, v89
	v_add_f32_e32 v61, v63, v83
	v_cvt_f32_f16_sdwa v63, v89 dst_sel:DWORD dst_unused:UNUSED_PAD src0_sel:WORD_1
	v_mul_f32_e32 v60, 0xbfb8aa3b, v60
	v_mul_f32_e32 v81, 0xbfb8aa3b, v62
	v_exp_f32_e32 v81, v81
	v_mul_f32_e32 v61, 0xbfb8aa3b, v61
	v_exp_f32_e32 v60, v60
	v_exp_f32_e32 v61, v61
	v_add_f32_e32 v81, 1.0, v81
	v_rcp_f32_e32 v82, v81
	v_mul_f32_e32 v81, 0xbfb8aa3b, v63
	v_exp_f32_e32 v81, v81
	v_add_f32_e32 v60, 1.0, v60
	v_add_f32_e32 v61, 1.0, v61
	v_rcp_f32_e32 v60, v60
	v_add_f32_e32 v81, 1.0, v81
	v_rcp_f32_e32 v61, v61
	v_rcp_f32_e32 v83, v81
	v_pk_mul_f32 v[60:61], v[86:87], v[60:61]
	v_pk_mul_f32 v[62:63], v[82:83], v[62:63]
	s_nop 0
	v_pk_mul_f32 v[60:61], v[60:61], v[62:63]
	s_nop 0
	v_cvt_pk_f16_f32 v81, v60, v61
	v_lshlrev_b64 v[60:61], 12, v[68:69]
	v_lshl_add_u64 v[60:61], s[8:9], 0, v[60:61]
	v_lshl_add_u64 v[60:61], v[60:61], 0, v[66:67]
	global_store_dwordx2 v[60:61], v[80:81], off
	global_load_dwordx4 v[80:83], v[64:65], off offset:64
	s_nop 0
	global_load_dwordx2 v[62:63], v[76:77], off offset:1056
	global_load_dwordx4 v[84:87], v[74:75], off offset:64
	s_waitcnt vmcnt(2)
	v_add_f32_e32 v56, v56, v80
	s_waitcnt vmcnt(1)
	v_cvt_f32_f16_e32 v80, v62
	v_add_f32_e32 v57, v57, v81
	v_cvt_f32_f16_sdwa v81, v62 dst_sel:DWORD dst_unused:UNUSED_PAD src0_sel:WORD_1
	v_mul_f32_e32 v56, 0xbfb8aa3b, v56
	v_mul_f32_e32 v62, 0xbfb8aa3b, v80
	v_exp_f32_e32 v62, v62
	v_mul_f32_e32 v57, 0xbfb8aa3b, v57
	v_exp_f32_e32 v56, v56
	v_exp_f32_e32 v57, v57
	v_add_f32_e32 v62, 1.0, v62
	v_rcp_f32_e32 v88, v62
	v_mul_f32_e32 v62, 0xbfb8aa3b, v81
	v_exp_f32_e32 v62, v62
	v_add_f32_e32 v56, 1.0, v56
	v_add_f32_e32 v57, 1.0, v57
	v_rcp_f32_e32 v56, v56
	v_add_f32_e32 v62, 1.0, v62
	v_rcp_f32_e32 v57, v57
	v_rcp_f32_e32 v89, v62
	v_cvt_f32_f16_e32 v62, v63
	v_cvt_f32_f16_sdwa v63, v63 dst_sel:DWORD dst_unused:UNUSED_PAD src0_sel:WORD_1
	s_waitcnt vmcnt(0)
	v_pk_mul_f32 v[56:57], v[84:85], v[56:57]
	v_pk_mul_f32 v[80:81], v[88:89], v[80:81]
	s_nop 0
	v_pk_mul_f32 v[56:57], v[56:57], v[80:81]
	s_nop 0
	v_cvt_pk_f16_f32 v56, v56, v57
	v_add_f32_e32 v57, v58, v82
	v_mul_f32_e32 v57, 0xbfb8aa3b, v57
	v_exp_f32_e32 v57, v57
	s_nop 0
	v_add_f32_e32 v57, 1.0, v57
	v_rcp_f32_e32 v58, v57
	v_add_f32_e32 v57, v59, v83
	v_mul_f32_e32 v57, 0xbfb8aa3b, v57
	v_exp_f32_e32 v57, v57
	s_nop 0
	v_add_f32_e32 v57, 1.0, v57
	v_rcp_f32_e32 v59, v57
	v_mul_f32_e32 v57, 0xbfb8aa3b, v62
	v_exp_f32_e32 v57, v57
	v_pk_mul_f32 v[58:59], v[86:87], v[58:59]
	v_add_f32_e32 v57, 1.0, v57
	v_rcp_f32_e32 v80, v57
	v_mul_f32_e32 v57, 0xbfb8aa3b, v63
	v_exp_f32_e32 v57, v57
	s_nop 0
	v_add_f32_e32 v57, 1.0, v57
	v_rcp_f32_e32 v81, v57
	s_nop 0
	v_pk_mul_f32 v[62:63], v[80:81], v[62:63]
	s_nop 0
	v_pk_mul_f32 v[58:59], v[58:59], v[62:63]
	s_nop 0
	v_cvt_pk_f16_f32 v57, v58, v59
	global_store_dwordx2 v[60:61], v[56:57], off offset:32
	global_load_dwordx4 v[56:59], v[64:65], off offset:128
	s_nop 0
	global_load_dwordx2 v[62:63], v[76:77], off offset:1088
	global_load_dwordx4 v[80:83], v[74:75], off offset:128
	s_waitcnt vmcnt(2)
	v_add_f32_e32 v52, v52, v56
	s_waitcnt vmcnt(1)
	v_cvt_f32_f16_e32 v56, v62
	v_add_f32_e32 v53, v53, v57
	v_cvt_f32_f16_sdwa v57, v62 dst_sel:DWORD dst_unused:UNUSED_PAD src0_sel:WORD_1
	v_mul_f32_e32 v52, 0xbfb8aa3b, v52
	v_mul_f32_e32 v62, 0xbfb8aa3b, v56
	v_exp_f32_e32 v62, v62
	v_mul_f32_e32 v53, 0xbfb8aa3b, v53
	v_exp_f32_e32 v52, v52
	v_exp_f32_e32 v53, v53
	v_add_f32_e32 v62, 1.0, v62
	v_rcp_f32_e32 v84, v62
	v_mul_f32_e32 v62, 0xbfb8aa3b, v57
	v_exp_f32_e32 v62, v62
	v_add_f32_e32 v52, 1.0, v52
	v_add_f32_e32 v53, 1.0, v53
	v_rcp_f32_e32 v52, v52
	v_add_f32_e32 v62, 1.0, v62
	v_rcp_f32_e32 v53, v53
	v_rcp_f32_e32 v85, v62
	s_waitcnt vmcnt(0)
	v_pk_mul_f32 v[52:53], v[80:81], v[52:53]
	v_pk_mul_f32 v[56:57], v[84:85], v[56:57]
	s_nop 0
	v_pk_mul_f32 v[52:53], v[52:53], v[56:57]
	v_cvt_f32_f16_e32 v56, v63
	v_cvt_pk_f16_f32 v52, v52, v53
	v_add_f32_e32 v53, v54, v58
	v_mul_f32_e32 v53, 0xbfb8aa3b, v53
	v_exp_f32_e32 v53, v53
	v_cvt_f32_f16_sdwa v57, v63 dst_sel:DWORD dst_unused:UNUSED_PAD src0_sel:WORD_1
	v_add_f32_e32 v53, 1.0, v53
	v_rcp_f32_e32 v54, v53
	v_add_f32_e32 v53, v55, v59
	v_mul_f32_e32 v53, 0xbfb8aa3b, v53
	v_exp_f32_e32 v53, v53
	s_nop 0
	v_add_f32_e32 v53, 1.0, v53
	v_rcp_f32_e32 v55, v53
	v_mul_f32_e32 v53, 0xbfb8aa3b, v56
	v_exp_f32_e32 v53, v53
	v_pk_mul_f32 v[54:55], v[82:83], v[54:55]
	v_add_f32_e32 v53, 1.0, v53
	v_rcp_f32_e32 v58, v53
	v_mul_f32_e32 v53, 0xbfb8aa3b, v57
	v_exp_f32_e32 v53, v53
	s_nop 0
	v_add_f32_e32 v53, 1.0, v53
	v_rcp_f32_e32 v59, v53
	s_nop 0
	v_pk_mul_f32 v[56:57], v[58:59], v[56:57]
	s_nop 0
	v_pk_mul_f32 v[54:55], v[54:55], v[56:57]
	s_nop 0
	v_cvt_pk_f16_f32 v53, v54, v55
	global_store_dwordx2 v[60:61], v[52:53], off offset:64
	global_load_dwordx4 v[52:55], v[64:65], off offset:192
	s_nop 0
	global_load_dwordx2 v[56:57], v[76:77], off offset:1120
	s_waitcnt vmcnt(1)
	v_add_f32_e32 v48, v48, v52
	global_load_dwordx4 v[74:77], v[74:75], off offset:192
	s_waitcnt vmcnt(1)
; DEV float sigmoid_f(float x) { return rcp_f(1.f + __expf(-x)); }
; DEV float silu_f(float x) { return x * rcp_f(1.f + __expf(-x)); }
; DEV void glu_item(const Params& p, const Ctx& cx, int l, int tile, char* smem) {
;     ...
;   small_gemm<512, 4>(p, cx, smem, 1040, Bt, (tid >> 6) * 64, [&](int m, int n, f32x4 v) {
;     int row = row0 + m;
;     float4 y = *(const float4*)(S5Y + (size_t)row * 512 + n);
;     float4 bb = *(const float4*)(bg + n);
;     h16x4 gt = *(const h16x4*)(zrest + (size_t)row * ZR + 512 + n);
;     uint2 o;
;     o.x = pack_bf2(y.x * sigmoid_f(v[0] + bb.x) * silu_f((float)gt[0]), y.y * sigmoid_f(v[1] + bb.y) * silu_f((float)gt[1]));
;     o.y = pack_bf2(y.z * sigmoid_f(v[2] + bb.z) * silu_f((float)gt[2]), y.w * sigmoid_f(v[3] + bb.w) * silu_f((float)gt[3]));
;     *(uint2*)(ym + (size_t)row * D + n) = o;
;   });
	v_cvt_f32_f16_e32 v52, v56
	v_add_f32_e32 v49, v49, v53
	v_cvt_f32_f16_sdwa v53, v56 dst_sel:DWORD dst_unused:UNUSED_PAD src0_sel:WORD_1
	v_mul_f32_e32 v48, 0xbfb8aa3b, v48
	v_mul_f32_e32 v56, 0xbfb8aa3b, v52
	v_exp_f32_e32 v56, v56
	v_mul_f32_e32 v49, 0xbfb8aa3b, v49
	v_exp_f32_e32 v48, v48
	v_exp_f32_e32 v49, v49
	v_add_f32_e32 v56, 1.0, v56
	v_rcp_f32_e32 v58, v56
	v_mul_f32_e32 v56, 0xbfb8aa3b, v53
	v_exp_f32_e32 v56, v56
	v_add_f32_e32 v48, 1.0, v48
	v_add_f32_e32 v49, 1.0, v49
	v_rcp_f32_e32 v48, v48
	v_add_f32_e32 v56, 1.0, v56
	v_rcp_f32_e32 v49, v49
	v_rcp_f32_e32 v59, v56
	v_or_b32_e32 v56, 16, v68
	v_pk_mul_f32 v[52:53], v[58:59], v[52:53]
	s_waitcnt vmcnt(0)
	v_pk_mul_f32 v[48:49], v[74:75], v[48:49]
	s_nop 0
	v_pk_mul_f32 v[48:49], v[48:49], v[52:53]
	v_cvt_f32_f16_e32 v52, v57
	v_cvt_pk_f16_f32 v48, v48, v49
	v_add_f32_e32 v49, v50, v54
	v_mul_f32_e32 v49, 0xbfb8aa3b, v49
	v_exp_f32_e32 v49, v49
	v_cvt_f32_f16_sdwa v53, v57 dst_sel:DWORD dst_unused:UNUSED_PAD src0_sel:WORD_1
	v_ashrrev_i32_e32 v57, 31, v56
	v_add_f32_e32 v49, 1.0, v49
	v_rcp_f32_e32 v50, v49
	v_add_f32_e32 v49, v51, v55
	v_mul_f32_e32 v49, 0xbfb8aa3b, v49
	v_exp_f32_e32 v49, v49
	s_nop 0
	v_add_f32_e32 v49, 1.0, v49
	v_rcp_f32_e32 v51, v49
	v_mul_f32_e32 v49, 0xbfb8aa3b, v52
	v_exp_f32_e32 v49, v49
	v_pk_mul_f32 v[50:51], v[76:77], v[50:51]
	v_add_f32_e32 v49, 1.0, v49
	v_rcp_f32_e32 v54, v49
	v_mul_f32_e32 v49, 0xbfb8aa3b, v53
	v_exp_f32_e32 v49, v49
	s_nop 0
	v_add_f32_e32 v49, 1.0, v49
	v_rcp_f32_e32 v55, v49
	s_nop 0
	v_pk_mul_f32 v[52:53], v[54:55], v[52:53]
	s_nop 0
	v_pk_mul_f32 v[50:51], v[50:51], v[52:53]
	v_mad_i64_i32 v[54:55], s[4:5], v56, s98, v[70:71]
	v_cvt_pk_f16_f32 v49, v50, v51
	global_store_dwordx2 v[60:61], v[48:49], off offset:96
	v_lshlrev_b64 v[48:49], 11, v[56:57]
	v_lshl_add_u64 v[48:49], s[22:23], 0, v[48:49]
	v_lshl_add_u64 v[54:55], v[54:55], 0, v[66:67]
	v_lshl_add_u64 v[52:53], v[48:49], 0, v[72:73]
	global_load_dwordx4 v[48:51], v[64:65], off
	global_load_dwordx2 v[58:59], v[54:55], off offset:1024
	global_load_dwordx4 v[60:63], v[52:53], off
	s_waitcnt vmcnt(2)
	v_add_f32_e32 v44, v44, v48
	s_waitcnt vmcnt(1)
	v_cvt_f32_f16_e32 v48, v58
	v_add_f32_e32 v45, v45, v49
	v_cvt_f32_f16_sdwa v49, v58 dst_sel:DWORD dst_unused:UNUSED_PAD src0_sel:WORD_1
	v_mul_f32_e32 v44, 0xbfb8aa3b, v44
	v_mul_f32_e32 v58, 0xbfb8aa3b, v48
	v_exp_f32_e32 v58, v58
	v_mul_f32_e32 v45, 0xbfb8aa3b, v45
	v_exp_f32_e32 v44, v44
	v_exp_f32_e32 v45, v45
	v_add_f32_e32 v58, 1.0, v58
	v_rcp_f32_e32 v74, v58
	v_mul_f32_e32 v58, 0xbfb8aa3b, v49
	v_exp_f32_e32 v58, v58
	v_add_f32_e32 v44, 1.0, v44
	v_add_f32_e32 v45, 1.0, v45
	v_rcp_f32_e32 v44, v44
	v_add_f32_e32 v58, 1.0, v58
	v_rcp_f32_e32 v45, v45
	v_rcp_f32_e32 v75, v58
	s_waitcnt vmcnt(0)
	v_pk_mul_f32 v[44:45], v[60:61], v[44:45]
	v_pk_mul_f32 v[48:49], v[74:75], v[48:49]
	s_nop 0
	v_pk_mul_f32 v[44:45], v[44:45], v[48:49]
	v_cvt_f32_f16_e32 v48, v59
	v_cvt_pk_f16_f32 v44, v44, v45
	v_add_f32_e32 v45, v46, v50
	v_mul_f32_e32 v45, 0xbfb8aa3b, v45
	v_exp_f32_e32 v45, v45
	v_cvt_f32_f16_sdwa v49, v59 dst_sel:DWORD dst_unused:UNUSED_PAD src0_sel:WORD_1
	v_add_f32_e32 v45, 1.0, v45
	v_rcp_f32_e32 v46, v45
	v_add_f32_e32 v45, v47, v51
	v_mul_f32_e32 v45, 0xbfb8aa3b, v45
	v_exp_f32_e32 v45, v45
	s_nop 0
	v_add_f32_e32 v45, 1.0, v45
	v_rcp_f32_e32 v47, v45
	v_mul_f32_e32 v45, 0xbfb8aa3b, v48
	v_exp_f32_e32 v45, v45
	v_pk_mul_f32 v[46:47], v[62:63], v[46:47]
	v_add_f32_e32 v45, 1.0, v45
	v_rcp_f32_e32 v50, v45
	v_mul_f32_e32 v45, 0xbfb8aa3b, v49
	v_exp_f32_e32 v45, v45
	s_nop 0
	v_add_f32_e32 v45, 1.0, v45
	v_rcp_f32_e32 v51, v45
	s_nop 0
	v_pk_mul_f32 v[48:49], v[50:51], v[48:49]
	s_nop 0
	v_pk_mul_f32 v[46:47], v[46:47], v[48:49]
	s_nop 0
	v_cvt_pk_f16_f32 v45, v46, v47
	v_lshlrev_b64 v[46:47], 12, v[56:57]
	v_lshl_add_u64 v[46:47], s[8:9], 0, v[46:47]
	v_lshl_add_u64 v[48:49], v[46:47], 0, v[66:67]
	global_store_dwordx2 v[48:49], v[44:45], off
	global_load_dwordx4 v[44:47], v[64:65], off offset:64
	s_nop 0
	global_load_dwordx2 v[50:51], v[54:55], off offset:1056
	global_load_dwordx4 v[56:59], v[52:53], off offset:64
	s_waitcnt vmcnt(2)
	v_add_f32_e32 v40, v40, v44
	s_waitcnt vmcnt(1)
	v_cvt_f32_f16_e32 v44, v50
	v_add_f32_e32 v41, v41, v45
	v_cvt_f32_f16_sdwa v45, v50 dst_sel:DWORD dst_unused:UNUSED_PAD src0_sel:WORD_1
	v_mul_f32_e32 v40, 0xbfb8aa3b, v40
	v_mul_f32_e32 v50, 0xbfb8aa3b, v44
	v_exp_f32_e32 v50, v50
	v_mul_f32_e32 v41, 0xbfb8aa3b, v41
	v_exp_f32_e32 v40, v40
	v_exp_f32_e32 v41, v41
	v_add_f32_e32 v50, 1.0, v50
	v_rcp_f32_e32 v60, v50
	v_mul_f32_e32 v50, 0xbfb8aa3b, v45
	v_exp_f32_e32 v50, v50
	v_add_f32_e32 v40, 1.0, v40
	v_add_f32_e32 v41, 1.0, v41
	v_rcp_f32_e32 v40, v40
	v_add_f32_e32 v50, 1.0, v50
	v_rcp_f32_e32 v41, v41
	v_rcp_f32_e32 v61, v50
	s_waitcnt vmcnt(0)
	v_pk_mul_f32 v[40:41], v[56:57], v[40:41]
	v_pk_mul_f32 v[44:45], v[60:61], v[44:45]
	s_nop 0
	v_pk_mul_f32 v[40:41], v[40:41], v[44:45]
	v_cvt_f32_f16_e32 v44, v51
	v_cvt_pk_f16_f32 v40, v40, v41
	v_add_f32_e32 v41, v42, v46
	v_mul_f32_e32 v41, 0xbfb8aa3b, v41
	v_exp_f32_e32 v41, v41
	v_cvt_f32_f16_sdwa v45, v51 dst_sel:DWORD dst_unused:UNUSED_PAD src0_sel:WORD_1
	v_add_f32_e32 v41, 1.0, v41
	v_rcp_f32_e32 v42, v41
	v_add_f32_e32 v41, v43, v47
	v_mul_f32_e32 v41, 0xbfb8aa3b, v41
	v_exp_f32_e32 v41, v41
	s_nop 0
	v_add_f32_e32 v41, 1.0, v41
	v_rcp_f32_e32 v43, v41
	v_mul_f32_e32 v41, 0xbfb8aa3b, v44
	v_exp_f32_e32 v41, v41
	v_pk_mul_f32 v[42:43], v[58:59], v[42:43]
	v_add_f32_e32 v41, 1.0, v41
	v_rcp_f32_e32 v46, v41
	v_mul_f32_e32 v41, 0xbfb8aa3b, v45
	v_exp_f32_e32 v41, v41
	s_nop 0
	v_add_f32_e32 v41, 1.0, v41
	v_rcp_f32_e32 v47, v41
	s_nop 0
	v_pk_mul_f32 v[44:45], v[46:47], v[44:45]
	s_nop 0
	v_pk_mul_f32 v[42:43], v[42:43], v[44:45]
	s_nop 0
	v_cvt_pk_f16_f32 v41, v42, v43
	global_store_dwordx2 v[48:49], v[40:41], off offset:32
	global_load_dwordx4 v[40:43], v[64:65], off offset:128
	s_nop 0
	global_load_dwordx2 v[44:45], v[54:55], off offset:1088
	global_load_dwordx4 v[56:59], v[52:53], off offset:128
	s_waitcnt vmcnt(2)
; DEV float sigmoid_f(float x) { return rcp_f(1.f + __expf(-x)); }
; DEV float silu_f(float x) { return x * rcp_f(1.f + __expf(-x)); }
; DEV void glu_item(const Params& p, const Ctx& cx, int l, int tile, char* smem) {
;     ...
;   small_gemm<512, 4>(p, cx, smem, 1040, Bt, (tid >> 6) * 64, [&](int m, int n, f32x4 v) {
;     int row = row0 + m;
;     float4 y = *(const float4*)(S5Y + (size_t)row * 512 + n);
;     float4 bb = *(const float4*)(bg + n);
;     h16x4 gt = *(const h16x4*)(zrest + (size_t)row * ZR + 512 + n);
;     uint2 o;
;     o.x = pack_bf2(y.x * sigmoid_f(v[0] + bb.x) * silu_f((float)gt[0]), y.y * sigmoid_f(v[1] + bb.y) * silu_f((float)gt[1]));
;     o.y = pack_bf2(y.z * sigmoid_f(v[2] + bb.z) * silu_f((float)gt[2]), y.w * sigmoid_f(v[3] + bb.w) * silu_f((float)gt[3]));
;     *(uint2*)(ym + (size_t)row * D + n) = o;
;   });
	v_add_f32_e32 v36, v36, v40
	s_waitcnt vmcnt(1)
	v_cvt_f32_f16_e32 v40, v44
	v_add_f32_e32 v37, v37, v41
	v_cvt_f32_f16_sdwa v41, v44 dst_sel:DWORD dst_unused:UNUSED_PAD src0_sel:WORD_1
	v_mul_f32_e32 v36, 0xbfb8aa3b, v36
	v_mul_f32_e32 v44, 0xbfb8aa3b, v40
	v_exp_f32_e32 v44, v44
	v_mul_f32_e32 v37, 0xbfb8aa3b, v37
	v_exp_f32_e32 v36, v36
	v_exp_f32_e32 v37, v37
	v_add_f32_e32 v44, 1.0, v44
	v_rcp_f32_e32 v46, v44
	v_mul_f32_e32 v44, 0xbfb8aa3b, v41
	v_exp_f32_e32 v44, v44
	v_add_f32_e32 v36, 1.0, v36
	v_add_f32_e32 v37, 1.0, v37
	v_rcp_f32_e32 v36, v36
	v_add_f32_e32 v44, 1.0, v44
	v_rcp_f32_e32 v37, v37
	v_rcp_f32_e32 v47, v44
	s_waitcnt vmcnt(0)
	v_pk_mul_f32 v[36:37], v[56:57], v[36:37]
	v_pk_mul_f32 v[40:41], v[46:47], v[40:41]
	s_nop 0
	v_pk_mul_f32 v[36:37], v[36:37], v[40:41]
	v_cvt_f32_f16_e32 v40, v45
	v_cvt_pk_f16_f32 v36, v36, v37
	v_add_f32_e32 v37, v38, v42
	v_mul_f32_e32 v37, 0xbfb8aa3b, v37
	v_exp_f32_e32 v37, v37
	v_cvt_f32_f16_sdwa v41, v45 dst_sel:DWORD dst_unused:UNUSED_PAD src0_sel:WORD_1
	v_add_f32_e32 v37, 1.0, v37
	v_rcp_f32_e32 v38, v37
	v_add_f32_e32 v37, v39, v43
	v_mul_f32_e32 v37, 0xbfb8aa3b, v37
	v_exp_f32_e32 v37, v37
	s_nop 0
	v_add_f32_e32 v37, 1.0, v37
	v_rcp_f32_e32 v39, v37
	v_mul_f32_e32 v37, 0xbfb8aa3b, v40
	v_exp_f32_e32 v37, v37
	v_pk_mul_f32 v[38:39], v[58:59], v[38:39]
	v_add_f32_e32 v37, 1.0, v37
	v_rcp_f32_e32 v42, v37
	v_mul_f32_e32 v37, 0xbfb8aa3b, v41
	v_exp_f32_e32 v37, v37
	s_nop 0
	v_add_f32_e32 v37, 1.0, v37
	v_rcp_f32_e32 v43, v37
	s_nop 0
	v_pk_mul_f32 v[40:41], v[42:43], v[40:41]
	s_nop 0
	v_pk_mul_f32 v[38:39], v[38:39], v[40:41]
	s_nop 0
	v_cvt_pk_f16_f32 v37, v38, v39
	global_store_dwordx2 v[48:49], v[36:37], off offset:64
	global_load_dwordx4 v[36:39], v[64:65], off offset:192
	s_nop 0
	global_load_dwordx2 v[40:41], v[54:55], off offset:1120
	global_load_dwordx4 v[42:45], v[52:53], off offset:192
	s_waitcnt vmcnt(2)
	v_add_f32_e32 v32, v32, v36
	s_waitcnt vmcnt(1)
	v_cvt_f32_f16_e32 v36, v40
	v_add_f32_e32 v33, v33, v37
	v_cvt_f32_f16_sdwa v37, v40 dst_sel:DWORD dst_unused:UNUSED_PAD src0_sel:WORD_1
	v_mul_f32_e32 v32, 0xbfb8aa3b, v32
	v_mul_f32_e32 v40, 0xbfb8aa3b, v36
	v_exp_f32_e32 v40, v40
	v_mul_f32_e32 v33, 0xbfb8aa3b, v33
	v_exp_f32_e32 v32, v32
	v_exp_f32_e32 v33, v33
	v_add_f32_e32 v40, 1.0, v40
	v_rcp_f32_e32 v46, v40
	v_mul_f32_e32 v40, 0xbfb8aa3b, v37
	v_exp_f32_e32 v40, v40
	v_add_f32_e32 v32, 1.0, v32
	v_add_f32_e32 v33, 1.0, v33
	v_rcp_f32_e32 v32, v32
	v_add_f32_e32 v40, 1.0, v40
	v_rcp_f32_e32 v33, v33
	v_rcp_f32_e32 v47, v40
	v_or_b32_e32 v40, 32, v68
	s_waitcnt vmcnt(0)
	v_pk_mul_f32 v[32:33], v[42:43], v[32:33]
	v_pk_mul_f32 v[36:37], v[46:47], v[36:37]
	s_nop 0
	v_pk_mul_f32 v[32:33], v[32:33], v[36:37]
	v_cvt_f32_f16_e32 v36, v41
	v_cvt_pk_f16_f32 v32, v32, v33
	v_add_f32_e32 v33, v34, v38
	v_mul_f32_e32 v33, 0xbfb8aa3b, v33
	v_exp_f32_e32 v33, v33
	v_cvt_f32_f16_sdwa v37, v41 dst_sel:DWORD dst_unused:UNUSED_PAD src0_sel:WORD_1
	v_ashrrev_i32_e32 v41, 31, v40
	v_add_f32_e32 v33, 1.0, v33
	v_rcp_f32_e32 v34, v33
	v_add_f32_e32 v33, v35, v39
	v_mul_f32_e32 v33, 0xbfb8aa3b, v33
	v_exp_f32_e32 v33, v33
	s_nop 0
	v_add_f32_e32 v33, 1.0, v33
	v_rcp_f32_e32 v35, v33
	v_mul_f32_e32 v33, 0xbfb8aa3b, v36
	v_exp_f32_e32 v33, v33
	v_pk_mul_f32 v[34:35], v[44:45], v[34:35]
	v_add_f32_e32 v33, 1.0, v33
	v_rcp_f32_e32 v38, v33
	v_mul_f32_e32 v33, 0xbfb8aa3b, v37
	v_exp_f32_e32 v33, v33
	s_nop 0
	v_add_f32_e32 v33, 1.0, v33
	v_rcp_f32_e32 v39, v33
	s_nop 0
	v_pk_mul_f32 v[36:37], v[38:39], v[36:37]
	s_nop 0
	v_pk_mul_f32 v[34:35], v[34:35], v[36:37]
	v_mad_i64_i32 v[38:39], s[4:5], v40, s98, v[70:71]
	v_cvt_pk_f16_f32 v33, v34, v35
	global_store_dwordx2 v[48:49], v[32:33], off offset:96
	v_lshlrev_b64 v[32:33], 11, v[40:41]
	v_lshl_add_u64 v[32:33], s[22:23], 0, v[32:33]
	v_lshl_add_u64 v[38:39], v[38:39], 0, v[66:67]
	v_lshl_add_u64 v[36:37], v[32:33], 0, v[72:73]
	global_load_dwordx4 v[32:35], v[64:65], off
	global_load_dwordx2 v[42:43], v[38:39], off offset:1024
	global_load_dwordx4 v[44:47], v[36:37], off
	s_waitcnt vmcnt(2)
	v_add_f32_e32 v28, v28, v32
	s_waitcnt vmcnt(1)
	v_cvt_f32_f16_e32 v32, v42
	v_add_f32_e32 v29, v29, v33
	v_cvt_f32_f16_sdwa v33, v42 dst_sel:DWORD dst_unused:UNUSED_PAD src0_sel:WORD_1
	v_mul_f32_e32 v28, 0xbfb8aa3b, v28
	v_mul_f32_e32 v42, 0xbfb8aa3b, v32
	v_exp_f32_e32 v42, v42
	v_mul_f32_e32 v29, 0xbfb8aa3b, v29
	v_exp_f32_e32 v28, v28
	v_exp_f32_e32 v29, v29
	v_add_f32_e32 v42, 1.0, v42
	v_rcp_f32_e32 v48, v42
	v_mul_f32_e32 v42, 0xbfb8aa3b, v33
	v_exp_f32_e32 v42, v42
	v_add_f32_e32 v28, 1.0, v28
	v_add_f32_e32 v29, 1.0, v29
	v_rcp_f32_e32 v28, v28
	v_add_f32_e32 v42, 1.0, v42
	v_rcp_f32_e32 v29, v29
	v_rcp_f32_e32 v49, v42
	s_waitcnt vmcnt(0)
	v_pk_mul_f32 v[28:29], v[44:45], v[28:29]
	v_pk_mul_f32 v[32:33], v[48:49], v[32:33]
	s_nop 0
	v_pk_mul_f32 v[28:29], v[28:29], v[32:33]
	v_cvt_f32_f16_e32 v32, v43
	v_cvt_pk_f16_f32 v28, v28, v29
	v_add_f32_e32 v29, v30, v34
	v_mul_f32_e32 v29, 0xbfb8aa3b, v29
	v_exp_f32_e32 v29, v29
	v_cvt_f32_f16_sdwa v33, v43 dst_sel:DWORD dst_unused:UNUSED_PAD src0_sel:WORD_1
	v_add_f32_e32 v29, 1.0, v29
	v_rcp_f32_e32 v30, v29
	v_add_f32_e32 v29, v31, v35
	v_mul_f32_e32 v29, 0xbfb8aa3b, v29
	v_exp_f32_e32 v29, v29
	s_nop 0
	v_add_f32_e32 v29, 1.0, v29
	v_rcp_f32_e32 v31, v29
	v_mul_f32_e32 v29, 0xbfb8aa3b, v32
	v_exp_f32_e32 v29, v29
	v_pk_mul_f32 v[30:31], v[46:47], v[30:31]
	v_add_f32_e32 v29, 1.0, v29
	v_rcp_f32_e32 v34, v29
	v_mul_f32_e32 v29, 0xbfb8aa3b, v33
	v_exp_f32_e32 v29, v29
	s_nop 0
	v_add_f32_e32 v29, 1.0, v29
	v_rcp_f32_e32 v35, v29
	s_nop 0
	v_pk_mul_f32 v[32:33], v[34:35], v[32:33]
	s_nop 0
	v_pk_mul_f32 v[30:31], v[30:31], v[32:33]
	s_nop 0
	v_cvt_pk_f16_f32 v29, v30, v31
	v_lshlrev_b64 v[30:31], 12, v[40:41]
	v_lshl_add_u64 v[30:31], s[8:9], 0, v[30:31]
	v_lshl_add_u64 v[32:33], v[30:31], 0, v[66:67]
	global_store_dwordx2 v[32:33], v[28:29], off
	global_load_dwordx4 v[28:31], v[64:65], off offset:64
	s_nop 0
	global_load_dwordx2 v[34:35], v[38:39], off offset:1056
	global_load_dwordx4 v[40:43], v[36:37], off offset:64
	s_waitcnt vmcnt(2)
; DEV float sigmoid_f(float x) { return rcp_f(1.f + __expf(-x)); }
; DEV float silu_f(float x) { return x * rcp_f(1.f + __expf(-x)); }
; DEV void glu_item(const Params& p, const Ctx& cx, int l, int tile, char* smem) {
;     ...
;   small_gemm<512, 4>(p, cx, smem, 1040, Bt, (tid >> 6) * 64, [&](int m, int n, f32x4 v) {
;     int row = row0 + m;
;     float4 y = *(const float4*)(S5Y + (size_t)row * 512 + n);
;     float4 bb = *(const float4*)(bg + n);
;     h16x4 gt = *(const h16x4*)(zrest + (size_t)row * ZR + 512 + n);
;     uint2 o;
;     o.x = pack_bf2(y.x * sigmoid_f(v[0] + bb.x) * silu_f((float)gt[0]), y.y * sigmoid_f(v[1] + bb.y) * silu_f((float)gt[1]));
;     o.y = pack_bf2(y.z * sigmoid_f(v[2] + bb.z) * silu_f((float)gt[2]), y.w * sigmoid_f(v[3] + bb.w) * silu_f((float)gt[3]));
;     *(uint2*)(ym + (size_t)row * D + n) = o;
;   });
	v_add_f32_e32 v24, v24, v28
	s_waitcnt vmcnt(1)
	v_cvt_f32_f16_e32 v28, v34
	v_add_f32_e32 v25, v25, v29
	v_cvt_f32_f16_sdwa v29, v34 dst_sel:DWORD dst_unused:UNUSED_PAD src0_sel:WORD_1
	v_mul_f32_e32 v24, 0xbfb8aa3b, v24
	v_mul_f32_e32 v34, 0xbfb8aa3b, v28
	v_exp_f32_e32 v34, v34
	v_mul_f32_e32 v25, 0xbfb8aa3b, v25
	v_exp_f32_e32 v24, v24
	v_exp_f32_e32 v25, v25
	v_add_f32_e32 v34, 1.0, v34
	v_rcp_f32_e32 v44, v34
	v_mul_f32_e32 v34, 0xbfb8aa3b, v29
	v_exp_f32_e32 v34, v34
	v_add_f32_e32 v24, 1.0, v24
	v_add_f32_e32 v25, 1.0, v25
	v_rcp_f32_e32 v24, v24
	v_add_f32_e32 v34, 1.0, v34
	v_rcp_f32_e32 v25, v25
	v_rcp_f32_e32 v45, v34
	s_waitcnt vmcnt(0)
	v_pk_mul_f32 v[24:25], v[40:41], v[24:25]
	v_pk_mul_f32 v[28:29], v[44:45], v[28:29]
	s_nop 0
	v_pk_mul_f32 v[24:25], v[24:25], v[28:29]
	v_cvt_f32_f16_e32 v28, v35
	v_cvt_pk_f16_f32 v24, v24, v25
	v_add_f32_e32 v25, v26, v30
	v_mul_f32_e32 v25, 0xbfb8aa3b, v25
	v_exp_f32_e32 v25, v25
	v_cvt_f32_f16_sdwa v29, v35 dst_sel:DWORD dst_unused:UNUSED_PAD src0_sel:WORD_1
	v_add_f32_e32 v25, 1.0, v25
	v_rcp_f32_e32 v26, v25
	v_add_f32_e32 v25, v27, v31
	v_mul_f32_e32 v25, 0xbfb8aa3b, v25
	v_exp_f32_e32 v25, v25
	s_nop 0
	v_add_f32_e32 v25, 1.0, v25
	v_rcp_f32_e32 v27, v25
	v_mul_f32_e32 v25, 0xbfb8aa3b, v28
	v_exp_f32_e32 v25, v25
	v_pk_mul_f32 v[26:27], v[42:43], v[26:27]
	v_add_f32_e32 v25, 1.0, v25
	v_rcp_f32_e32 v30, v25
	v_mul_f32_e32 v25, 0xbfb8aa3b, v29
	v_exp_f32_e32 v25, v25
	s_nop 0
	v_add_f32_e32 v25, 1.0, v25
	v_rcp_f32_e32 v31, v25
	s_nop 0
	v_pk_mul_f32 v[28:29], v[30:31], v[28:29]
	s_nop 0
	v_pk_mul_f32 v[26:27], v[26:27], v[28:29]
	s_nop 0
	v_cvt_pk_f16_f32 v25, v26, v27
	global_store_dwordx2 v[32:33], v[24:25], off offset:32
	global_load_dwordx4 v[24:27], v[64:65], off offset:128
	s_nop 0
	global_load_dwordx2 v[28:29], v[38:39], off offset:1088
	global_load_dwordx4 v[40:43], v[36:37], off offset:128
	s_waitcnt vmcnt(2)
	v_add_f32_e32 v20, v20, v24
	s_waitcnt vmcnt(1)
	v_cvt_f32_f16_e32 v24, v28
	v_add_f32_e32 v21, v21, v25
	v_cvt_f32_f16_sdwa v25, v28 dst_sel:DWORD dst_unused:UNUSED_PAD src0_sel:WORD_1
	v_mul_f32_e32 v20, 0xbfb8aa3b, v20
	v_mul_f32_e32 v28, 0xbfb8aa3b, v24
	v_exp_f32_e32 v28, v28
	v_mul_f32_e32 v21, 0xbfb8aa3b, v21
	v_exp_f32_e32 v20, v20
	v_exp_f32_e32 v21, v21
	v_add_f32_e32 v28, 1.0, v28
	v_rcp_f32_e32 v30, v28
	v_mul_f32_e32 v28, 0xbfb8aa3b, v25
	v_exp_f32_e32 v28, v28
	v_add_f32_e32 v20, 1.0, v20
	v_add_f32_e32 v21, 1.0, v21
	v_rcp_f32_e32 v20, v20
	v_add_f32_e32 v28, 1.0, v28
	v_rcp_f32_e32 v21, v21
	v_rcp_f32_e32 v31, v28
	s_waitcnt vmcnt(0)
	v_pk_mul_f32 v[20:21], v[40:41], v[20:21]
	v_pk_mul_f32 v[24:25], v[30:31], v[24:25]
	s_nop 0
	v_pk_mul_f32 v[20:21], v[20:21], v[24:25]
	v_cvt_f32_f16_e32 v24, v29
	v_cvt_pk_f16_f32 v20, v20, v21
	v_add_f32_e32 v21, v22, v26
	v_mul_f32_e32 v21, 0xbfb8aa3b, v21
	v_exp_f32_e32 v21, v21
	v_cvt_f32_f16_sdwa v25, v29 dst_sel:DWORD dst_unused:UNUSED_PAD src0_sel:WORD_1
	v_add_f32_e32 v21, 1.0, v21
	v_rcp_f32_e32 v22, v21
	v_add_f32_e32 v21, v23, v27
	v_mul_f32_e32 v21, 0xbfb8aa3b, v21
	v_exp_f32_e32 v21, v21
	s_nop 0
	v_add_f32_e32 v21, 1.0, v21
	v_rcp_f32_e32 v23, v21
	v_mul_f32_e32 v21, 0xbfb8aa3b, v24
	v_exp_f32_e32 v21, v21
	v_pk_mul_f32 v[22:23], v[42:43], v[22:23]
	v_add_f32_e32 v21, 1.0, v21
	v_rcp_f32_e32 v26, v21
	v_mul_f32_e32 v21, 0xbfb8aa3b, v25
	v_exp_f32_e32 v21, v21
	s_nop 0
	v_add_f32_e32 v21, 1.0, v21
	v_rcp_f32_e32 v27, v21
	s_nop 0
	v_pk_mul_f32 v[24:25], v[26:27], v[24:25]
	s_nop 0
	v_pk_mul_f32 v[22:23], v[22:23], v[24:25]
	s_nop 0
	v_cvt_pk_f16_f32 v21, v22, v23
	global_store_dwordx2 v[32:33], v[20:21], off offset:64
	global_load_dwordx4 v[20:23], v[64:65], off offset:192
	s_nop 0
	global_load_dwordx2 v[24:25], v[38:39], off offset:1120
	global_load_dwordx4 v[26:29], v[36:37], off offset:192
	s_waitcnt vmcnt(2)
	v_add_f32_e32 v16, v16, v20
	s_waitcnt vmcnt(1)
	v_cvt_f32_f16_e32 v20, v24
	v_add_f32_e32 v17, v17, v21
	v_cvt_f32_f16_sdwa v21, v24 dst_sel:DWORD dst_unused:UNUSED_PAD src0_sel:WORD_1
	v_mul_f32_e32 v16, 0xbfb8aa3b, v16
	v_mul_f32_e32 v24, 0xbfb8aa3b, v20
	v_exp_f32_e32 v24, v24
	v_mul_f32_e32 v17, 0xbfb8aa3b, v17
	v_exp_f32_e32 v16, v16
	v_exp_f32_e32 v17, v17
	v_add_f32_e32 v24, 1.0, v24
	v_rcp_f32_e32 v30, v24
	v_mul_f32_e32 v24, 0xbfb8aa3b, v21
	v_exp_f32_e32 v24, v24
	v_add_f32_e32 v16, 1.0, v16
	v_add_f32_e32 v17, 1.0, v17
	v_rcp_f32_e32 v16, v16
	v_add_f32_e32 v24, 1.0, v24
	v_rcp_f32_e32 v17, v17
	v_rcp_f32_e32 v31, v24
	v_or_b32_e32 v24, 48, v68
	s_waitcnt vmcnt(0)
	v_pk_mul_f32 v[16:17], v[26:27], v[16:17]
	v_pk_mul_f32 v[20:21], v[30:31], v[20:21]
	s_nop 0
	v_pk_mul_f32 v[16:17], v[16:17], v[20:21]
	v_cvt_f32_f16_e32 v20, v25
	v_cvt_pk_f16_f32 v16, v16, v17
	v_add_f32_e32 v17, v18, v22
	v_mul_f32_e32 v17, 0xbfb8aa3b, v17
	v_exp_f32_e32 v17, v17
	v_cvt_f32_f16_sdwa v21, v25 dst_sel:DWORD dst_unused:UNUSED_PAD src0_sel:WORD_1
	v_ashrrev_i32_e32 v25, 31, v24
	v_add_f32_e32 v17, 1.0, v17
	v_rcp_f32_e32 v18, v17
	v_add_f32_e32 v17, v19, v23
	v_mul_f32_e32 v17, 0xbfb8aa3b, v17
	v_exp_f32_e32 v17, v17
	s_nop 0
	v_add_f32_e32 v17, 1.0, v17
	v_rcp_f32_e32 v19, v17
	v_mul_f32_e32 v17, 0xbfb8aa3b, v20
	v_exp_f32_e32 v17, v17
	v_pk_mul_f32 v[18:19], v[28:29], v[18:19]
	v_add_f32_e32 v17, 1.0, v17
	v_rcp_f32_e32 v22, v17
	v_mul_f32_e32 v17, 0xbfb8aa3b, v21
	v_exp_f32_e32 v17, v17
	s_nop 0
	v_add_f32_e32 v17, 1.0, v17
	v_rcp_f32_e32 v23, v17
	s_nop 0
	v_pk_mul_f32 v[20:21], v[22:23], v[20:21]
	s_nop 0
	v_pk_mul_f32 v[18:19], v[18:19], v[20:21]
	v_mad_i64_i32 v[20:21], s[4:5], v24, s98, v[70:71]
	v_cvt_pk_f16_f32 v17, v18, v19
	global_store_dwordx2 v[32:33], v[16:17], off offset:96
	v_lshlrev_b64 v[16:17], 11, v[24:25]
	v_lshl_add_u64 v[16:17], s[22:23], 0, v[16:17]
	v_lshl_add_u64 v[20:21], v[20:21], 0, v[66:67]
	v_lshl_add_u64 v[22:23], v[16:17], 0, v[72:73]
	global_load_dwordx4 v[16:19], v[64:65], off
	global_load_dwordx2 v[26:27], v[20:21], off offset:1024
	global_load_dwordx4 v[28:31], v[22:23], off
	s_mov_b32 s23, 0x8000
	s_waitcnt vmcnt(2)
; DEV float sigmoid_f(float x) { return rcp_f(1.f + __expf(-x)); }
; DEV float silu_f(float x) { return x * rcp_f(1.f + __expf(-x)); }
; DEV void glu_item(const Params& p, const Ctx& cx, int l, int tile, char* smem) {
;     ...
;   small_gemm<512, 4>(p, cx, smem, 1040, Bt, (tid >> 6) * 64, [&](int m, int n, f32x4 v) {
;     int row = row0 + m;
;     float4 y = *(const float4*)(S5Y + (size_t)row * 512 + n);
;     float4 bb = *(const float4*)(bg + n);
;     h16x4 gt = *(const h16x4*)(zrest + (size_t)row * ZR + 512 + n);
;     uint2 o;
;     o.x = pack_bf2(y.x * sigmoid_f(v[0] + bb.x) * silu_f((float)gt[0]), y.y * sigmoid_f(v[1] + bb.y) * silu_f((float)gt[1]));
;     o.y = pack_bf2(y.z * sigmoid_f(v[2] + bb.z) * silu_f((float)gt[2]), y.w * sigmoid_f(v[3] + bb.w) * silu_f((float)gt[3]));
;     *(uint2*)(ym + (size_t)row * D + n) = o;
;   });
	v_add_f32_e32 v12, v12, v16
	s_waitcnt vmcnt(1)
	v_cvt_f32_f16_e32 v16, v26
	v_add_f32_e32 v13, v13, v17
	v_cvt_f32_f16_sdwa v17, v26 dst_sel:DWORD dst_unused:UNUSED_PAD src0_sel:WORD_1
	v_mul_f32_e32 v12, 0xbfb8aa3b, v12
	v_mul_f32_e32 v26, 0xbfb8aa3b, v16
	v_exp_f32_e32 v26, v26
	v_mul_f32_e32 v13, 0xbfb8aa3b, v13
	v_exp_f32_e32 v12, v12
	v_exp_f32_e32 v13, v13
	v_add_f32_e32 v26, 1.0, v26
	v_rcp_f32_e32 v32, v26
	v_mul_f32_e32 v26, 0xbfb8aa3b, v17
	v_exp_f32_e32 v26, v26
	v_add_f32_e32 v12, 1.0, v12
	v_add_f32_e32 v13, 1.0, v13
	v_rcp_f32_e32 v12, v12
	v_add_f32_e32 v26, 1.0, v26
	v_rcp_f32_e32 v13, v13
	v_rcp_f32_e32 v33, v26
	s_waitcnt vmcnt(0)
	v_pk_mul_f32 v[12:13], v[28:29], v[12:13]
	v_pk_mul_f32 v[16:17], v[32:33], v[16:17]
	s_nop 0
	v_pk_mul_f32 v[12:13], v[12:13], v[16:17]
	v_cvt_f32_f16_e32 v16, v27
	v_cvt_pk_f16_f32 v12, v12, v13
	v_add_f32_e32 v13, v14, v18
	v_mul_f32_e32 v13, 0xbfb8aa3b, v13
	v_exp_f32_e32 v13, v13
	v_cvt_f32_f16_sdwa v17, v27 dst_sel:DWORD dst_unused:UNUSED_PAD src0_sel:WORD_1
	v_add_f32_e32 v13, 1.0, v13
	v_rcp_f32_e32 v14, v13
	v_add_f32_e32 v13, v15, v19
	v_mul_f32_e32 v13, 0xbfb8aa3b, v13
	v_exp_f32_e32 v13, v13
	s_nop 0
	v_add_f32_e32 v13, 1.0, v13
	v_rcp_f32_e32 v15, v13
	v_mul_f32_e32 v13, 0xbfb8aa3b, v16
	v_exp_f32_e32 v13, v13
	v_pk_mul_f32 v[14:15], v[30:31], v[14:15]
	v_add_f32_e32 v13, 1.0, v13
	v_rcp_f32_e32 v18, v13
	v_mul_f32_e32 v13, 0xbfb8aa3b, v17
	v_exp_f32_e32 v13, v13
	s_nop 0
	v_add_f32_e32 v13, 1.0, v13
	v_rcp_f32_e32 v19, v13
	s_nop 0
	v_pk_mul_f32 v[16:17], v[18:19], v[16:17]
	s_nop 0
	v_pk_mul_f32 v[14:15], v[14:15], v[16:17]
	s_nop 0
	v_cvt_pk_f16_f32 v13, v14, v15
	v_lshlrev_b64 v[14:15], 12, v[24:25]
	v_lshl_add_u64 v[14:15], s[8:9], 0, v[14:15]
	v_lshl_add_u64 v[16:17], v[14:15], 0, v[66:67]
	global_store_dwordx2 v[16:17], v[12:13], off
	global_load_dwordx4 v[12:15], v[64:65], off offset:64
	s_nop 0
	global_load_dwordx2 v[18:19], v[20:21], off offset:1056
	global_load_dwordx4 v[24:27], v[22:23], off offset:64
	s_waitcnt vmcnt(2)
	v_add_f32_e32 v8, v8, v12
	s_waitcnt vmcnt(1)
	v_cvt_f32_f16_e32 v12, v18
	v_add_f32_e32 v9, v9, v13
	v_cvt_f32_f16_sdwa v13, v18 dst_sel:DWORD dst_unused:UNUSED_PAD src0_sel:WORD_1
	v_mul_f32_e32 v8, 0xbfb8aa3b, v8
	v_mul_f32_e32 v18, 0xbfb8aa3b, v12
	v_exp_f32_e32 v18, v18
	v_mul_f32_e32 v9, 0xbfb8aa3b, v9
	v_exp_f32_e32 v8, v8
	v_exp_f32_e32 v9, v9
	v_add_f32_e32 v18, 1.0, v18
	v_rcp_f32_e32 v28, v18
	v_mul_f32_e32 v18, 0xbfb8aa3b, v13
	v_exp_f32_e32 v18, v18
	v_add_f32_e32 v8, 1.0, v8
	v_add_f32_e32 v9, 1.0, v9
	v_rcp_f32_e32 v8, v8
	v_add_f32_e32 v18, 1.0, v18
	v_rcp_f32_e32 v9, v9
	v_rcp_f32_e32 v29, v18
	s_waitcnt vmcnt(0)
	v_pk_mul_f32 v[8:9], v[24:25], v[8:9]
	v_pk_mul_f32 v[12:13], v[28:29], v[12:13]
	s_nop 0
	v_pk_mul_f32 v[8:9], v[8:9], v[12:13]
	v_cvt_f32_f16_e32 v12, v19
	v_cvt_pk_f16_f32 v8, v8, v9
	v_add_f32_e32 v9, v10, v14
	v_mul_f32_e32 v9, 0xbfb8aa3b, v9
	v_exp_f32_e32 v9, v9
	v_cvt_f32_f16_sdwa v13, v19 dst_sel:DWORD dst_unused:UNUSED_PAD src0_sel:WORD_1
	v_add_f32_e32 v9, 1.0, v9
	v_rcp_f32_e32 v10, v9
	v_add_f32_e32 v9, v11, v15
	v_mul_f32_e32 v9, 0xbfb8aa3b, v9
	v_exp_f32_e32 v9, v9
	s_nop 0
	v_add_f32_e32 v9, 1.0, v9
	v_rcp_f32_e32 v11, v9
	v_mul_f32_e32 v9, 0xbfb8aa3b, v12
	v_exp_f32_e32 v9, v9
	v_pk_mul_f32 v[10:11], v[26:27], v[10:11]
	v_add_f32_e32 v9, 1.0, v9
	v_rcp_f32_e32 v14, v9
	v_mul_f32_e32 v9, 0xbfb8aa3b, v13
	v_exp_f32_e32 v9, v9
	s_nop 0
	v_add_f32_e32 v9, 1.0, v9
	v_rcp_f32_e32 v15, v9
	s_nop 0
	v_pk_mul_f32 v[12:13], v[14:15], v[12:13]
	s_nop 0
	v_pk_mul_f32 v[10:11], v[10:11], v[12:13]
	s_nop 0
	v_cvt_pk_f16_f32 v9, v10, v11
	global_store_dwordx2 v[16:17], v[8:9], off offset:32
	global_load_dwordx4 v[8:11], v[64:65], off offset:128
	s_nop 0
	global_load_dwordx2 v[12:13], v[20:21], off offset:1088
	global_load_dwordx4 v[24:27], v[22:23], off offset:128
	s_waitcnt vmcnt(2)
; DEV float sigmoid_f(float x) { return rcp_f(1.f + __expf(-x)); }
; DEV float silu_f(float x) { return x * rcp_f(1.f + __expf(-x)); }
; DEV void glu_item(const Params& p, const Ctx& cx, int l, int tile, char* smem) {
;     ...
;   small_gemm<512, 4>(p, cx, smem, 1040, Bt, (tid >> 6) * 64, [&](int m, int n, f32x4 v) {
;     int row = row0 + m;
;     float4 y = *(const float4*)(S5Y + (size_t)row * 512 + n);
;     float4 bb = *(const float4*)(bg + n);
;     h16x4 gt = *(const h16x4*)(zrest + (size_t)row * ZR + 512 + n);
;     uint2 o;
;     o.x = pack_bf2(y.x * sigmoid_f(v[0] + bb.x) * silu_f((float)gt[0]), y.y * sigmoid_f(v[1] + bb.y) * silu_f((float)gt[1]));
;     o.y = pack_bf2(y.z * sigmoid_f(v[2] + bb.z) * silu_f((float)gt[2]), y.w * sigmoid_f(v[3] + bb.w) * silu_f((float)gt[3]));
;     *(uint2*)(ym + (size_t)row * D + n) = o;
;   });
	v_add_f32_e32 v4, v4, v8
	s_waitcnt vmcnt(1)
	v_cvt_f32_f16_e32 v8, v12
	v_add_f32_e32 v5, v5, v9
	v_cvt_f32_f16_sdwa v9, v12 dst_sel:DWORD dst_unused:UNUSED_PAD src0_sel:WORD_1
	v_mul_f32_e32 v4, 0xbfb8aa3b, v4
	v_mul_f32_e32 v12, 0xbfb8aa3b, v8
	v_exp_f32_e32 v12, v12
	v_mul_f32_e32 v5, 0xbfb8aa3b, v5
	v_exp_f32_e32 v4, v4
	v_exp_f32_e32 v5, v5
	v_add_f32_e32 v12, 1.0, v12
	v_rcp_f32_e32 v14, v12
	v_mul_f32_e32 v12, 0xbfb8aa3b, v9
	v_exp_f32_e32 v12, v12
	v_add_f32_e32 v4, 1.0, v4
	v_add_f32_e32 v5, 1.0, v5
	v_rcp_f32_e32 v4, v4
	v_add_f32_e32 v12, 1.0, v12
	v_rcp_f32_e32 v5, v5
	v_rcp_f32_e32 v15, v12
	s_waitcnt vmcnt(0)
	v_pk_mul_f32 v[4:5], v[24:25], v[4:5]
	v_pk_mul_f32 v[8:9], v[14:15], v[8:9]
	s_nop 0
	v_pk_mul_f32 v[4:5], v[4:5], v[8:9]
	v_cvt_f32_f16_e32 v8, v13
	v_cvt_pk_f16_f32 v4, v4, v5
	v_add_f32_e32 v5, v6, v10
	v_mul_f32_e32 v5, 0xbfb8aa3b, v5
	v_exp_f32_e32 v5, v5
	v_cvt_f32_f16_sdwa v9, v13 dst_sel:DWORD dst_unused:UNUSED_PAD src0_sel:WORD_1
	v_add_f32_e32 v5, 1.0, v5
	v_rcp_f32_e32 v6, v5
	v_add_f32_e32 v5, v7, v11
	v_mul_f32_e32 v5, 0xbfb8aa3b, v5
	v_exp_f32_e32 v5, v5
	s_nop 0
	v_add_f32_e32 v5, 1.0, v5
	v_rcp_f32_e32 v7, v5
	v_mul_f32_e32 v5, 0xbfb8aa3b, v8
	v_exp_f32_e32 v5, v5
	v_pk_mul_f32 v[6:7], v[26:27], v[6:7]
	v_add_f32_e32 v5, 1.0, v5
	v_rcp_f32_e32 v10, v5
	v_mul_f32_e32 v5, 0xbfb8aa3b, v9
	v_exp_f32_e32 v5, v5
	s_nop 0
	v_add_f32_e32 v5, 1.0, v5
	v_rcp_f32_e32 v11, v5
	s_nop 0
	v_pk_mul_f32 v[8:9], v[10:11], v[8:9]
	s_nop 0
	v_pk_mul_f32 v[6:7], v[6:7], v[8:9]
	s_nop 0
	v_cvt_pk_f16_f32 v5, v6, v7
	global_store_dwordx2 v[16:17], v[4:5], off offset:64
	global_load_dwordx4 v[4:7], v[22:23], off offset:192
	s_nop 0
	global_load_dwordx4 v[8:11], v[64:65], off offset:192
	global_load_dwordx2 v[12:13], v[20:21], off offset:1120
	s_waitcnt vmcnt(1)
	v_add_f32_e32 v0, v0, v8
	v_add_f32_e32 v1, v1, v9
	v_mul_f32_e32 v0, 0xbfb8aa3b, v0
	v_mul_f32_e32 v1, 0xbfb8aa3b, v1
	v_exp_f32_e32 v0, v0
	v_exp_f32_e32 v1, v1
	s_waitcnt vmcnt(0)
	v_cvt_f32_f16_e32 v8, v12
	v_cvt_f32_f16_sdwa v9, v12 dst_sel:DWORD dst_unused:UNUSED_PAD src0_sel:WORD_1
	v_add_f32_e32 v0, 1.0, v0
	v_add_f32_e32 v1, 1.0, v1
	v_rcp_f32_e32 v0, v0
	v_rcp_f32_e32 v1, v1
	v_mul_f32_e32 v12, 0xbfb8aa3b, v8
	v_exp_f32_e32 v12, v12
	v_pk_mul_f32 v[0:1], v[4:5], v[0:1]
	v_mul_f32_e32 v4, 0xbfb8aa3b, v9
	v_exp_f32_e32 v4, v4
	v_add_f32_e32 v12, 1.0, v12
	v_rcp_f32_e32 v14, v12
	v_add_f32_e32 v4, 1.0, v4
	v_rcp_f32_e32 v15, v4
	s_nop 0
	v_pk_mul_f32 v[4:5], v[14:15], v[8:9]
	s_nop 0
	v_pk_mul_f32 v[0:1], v[0:1], v[4:5]
	v_mov_b32_e32 v4, v6
	v_cvt_pk_f16_f32 v8, v0, v1
	v_cvt_f32_f16_e32 v1, v13
	v_add_f32_e32 v0, v2, v10
	v_mul_f32_e32 v0, 0xbfb8aa3b, v0
	v_exp_f32_e32 v0, v0
	v_mul_f32_e32 v2, 0xbfb8aa3b, v1
	v_exp_f32_e32 v2, v2
	global_store_dword v[16:17], v8, off offset:96
	v_add_f32_e32 v0, 1.0, v0
	v_rcp_f32_e32 v0, v0
	v_add_f32_e32 v2, 1.0, v2
	v_rcp_f32_e32 v5, v2
	s_nop 0
	v_pk_mul_f32 v[0:1], v[4:5], v[0:1]
	s_nop 0
	v_mul_f32_e32 v4, v0, v1
	v_cvt_f32_f16_sdwa v1, v13 dst_sel:DWORD dst_unused:UNUSED_PAD src0_sel:WORD_1
	v_add_f32_e32 v0, v3, v11
	v_mul_f32_e32 v0, 0xbfb8aa3b, v0
	v_exp_f32_e32 v0, v0
	v_mul_f32_e32 v2, 0xbfb8aa3b, v1
	v_exp_f32_e32 v2, v2
	v_add_f32_e32 v0, 1.0, v0
	v_rcp_f32_e32 v0, v0
	v_add_f32_e32 v2, 1.0, v2
	v_rcp_f32_e32 v3, v2
	v_mov_b32_e32 v2, v7
	v_pk_mul_f32 v[0:1], v[2:3], v[0:1]
	s_nop 0
	v_mul_f32_e32 v0, v0, v1
	v_cvt_pk_f16_f32 v2, v4, v0
	v_lshl_add_u64 v[0:1], v[16:17], 0, s[84:85]
	s_mov_b64 s[84:85], -1
	s_and_b64 vcc, exec, s[38:39]
	s_cbranch_vccz .LBB0_146
	s_branch .LBB0_141
